# N3: N2 + the w_in K-loop also skips the dummy next-unit prefetch DMAs in the final (half) unit's last iteration
# baseline (speedup 1.0000x reference)
.Lk0_half1:
	s_setprio 0
	s_barrier
	s_add_i32 s85, s85, s39
	v_lshl_add_u64 v[182:183], s[6:7], 0, v[80:81]
	s_mov_b32 m0, s85
	ds_read_b128 v[174:177], v145 offset:16384
	ds_read_b128 v[178:181], v145 offset:17408
	ds_read_b128 v[200:203], v145 offset:18432
	ds_read_b128 v[204:207], v145 offset:19456
	ds_read_b128 v[208:211], v145 offset:20480
	ds_read_b128 v[212:215], v145 offset:21504
	ds_read_b128 v[222:225], v145 offset:22528
	ds_read_b128 v[226:229], v145 offset:23552
	s_cmp_lg_u64 s[36:37], 0
	s_cbranch_scc1 .Ln3_w2_do
	s_cmp_eq_u32 s84, 12
	s_cbranch_scc1 .Ln3_w2
.Ln3_w2_do:
	global_load_lds_dwordx4 v[182:183], off
	s_add_i32 m0, s85, 0x2000
	s_add_u32 s86, s6, 0x40000
	v_lshl_add_u64 v[184:185], s[6:7], 0, v[130:131]
	s_addc_u32 s87, s7, 0
	s_add_i32 s85, s88, s39
	global_load_lds_dwordx4 v[184:185], off
	v_lshl_add_u64 v[188:189], s[86:87], 0, v[80:81]
	s_mov_b32 m0, s85
	v_lshl_add_u64 v[190:191], s[30:31], 0, v[132:133]
	s_cmp_eq_u32 s101, 1
	s_cbranch_scc1 .Lk0_nb1a
	global_load_lds_dwordx4 v[188:189], off
	v_lshl_add_u64 v[188:189], s[86:87], 0, v[130:131]
	s_add_i32 m0, s85, 0x2000
	s_nop 0
	global_load_lds_dwordx4 v[188:189], off
.Lk0_nb1a:
	v_lshl_add_u64 v[188:189], s[30:31], 0, v[134:135]
	s_mov_b32 m0, s60
	s_nop 0
	global_load_lds_dwordx4 v[188:189], off
	s_mov_b32 m0, s61
	s_nop 0
	global_load_lds_dwordx4 v[190:191], off
	s_waitcnt vmcnt(8)
	s_cmp_lg_u32 s101, 1
	s_cbranch_scc1 .Lk0_w2
	s_waitcnt vmcnt(6)
.Lk0_w2:
	s_branch .Ln3_w2_j
.Ln3_w2:
	s_waitcnt vmcnt(2)
.Ln3_w2_j:
	s_waitcnt lgkmcnt(0)
	s_barrier
	s_setprio 1
	s_waitcnt lgkmcnt(0)
	s_cmp_eq_u32 s101, 1
	v_mfma_f32_16x16x32_bf16 v[60:63], v[140:143], v[174:177], v[60:63]
	v_mfma_f32_16x16x32_bf16 v[56:59], v[150:153], v[174:177], v[56:59]
	v_mfma_f32_16x16x32_bf16 v[48:51], v[140:143], v[200:203], v[48:51]
	v_mfma_f32_16x16x32_bf16 v[40:43], v[150:153], v[200:203], v[40:43]
	v_mfma_f32_16x16x32_bf16 v[32:35], v[140:143], v[208:211], v[32:35]
	v_mfma_f32_16x16x32_bf16 v[24:27], v[150:153], v[208:211], v[24:27]
	v_mfma_f32_16x16x32_bf16 v[16:19], v[140:143], v[222:225], v[16:19]
	v_mfma_f32_16x16x32_bf16 v[8:11], v[150:153], v[222:225], v[8:11]
	v_mfma_f32_16x16x32_bf16 v[60:63], v[146:149], v[178:181], v[60:63]
	v_mfma_f32_16x16x32_bf16 v[56:59], v[154:157], v[178:181], v[56:59]
	v_mfma_f32_16x16x32_bf16 v[48:51], v[146:149], v[204:207], v[48:51]
	v_mfma_f32_16x16x32_bf16 v[40:43], v[154:157], v[204:207], v[40:43]
	v_mfma_f32_16x16x32_bf16 v[32:35], v[146:149], v[212:215], v[32:35]
	v_mfma_f32_16x16x32_bf16 v[24:27], v[154:157], v[212:215], v[24:27]
	v_mfma_f32_16x16x32_bf16 v[16:19], v[146:149], v[226:229], v[16:19]
	v_mfma_f32_16x16x32_bf16 v[8:11], v[154:157], v[226:229], v[8:11]
	s_cbranch_scc1 .Lk0_half2
	v_mfma_f32_16x16x32_bf16 v[52:55], v[158:161], v[174:177], v[52:55]
	v_mfma_f32_16x16x32_bf16 v[44:47], v[166:169], v[174:177], v[44:47]
	v_mfma_f32_16x16x32_bf16 v[36:39], v[158:161], v[200:203], v[36:39]
	v_mfma_f32_16x16x32_bf16 v[28:31], v[166:169], v[200:203], v[28:31]
	v_mfma_f32_16x16x32_bf16 v[20:23], v[158:161], v[208:211], v[20:23]
	v_mfma_f32_16x16x32_bf16 v[12:15], v[166:169], v[208:211], v[12:15]
	v_mfma_f32_16x16x32_bf16 v[4:7], v[158:161], v[222:225], v[4:7]
	v_mfma_f32_16x16x32_bf16 v[0:3], v[166:169], v[222:225], v[0:3]
	v_mfma_f32_16x16x32_bf16 v[52:55], v[162:165], v[178:181], v[52:55]
	v_mfma_f32_16x16x32_bf16 v[44:47], v[170:173], v[178:181], v[44:47]
	v_mfma_f32_16x16x32_bf16 v[36:39], v[162:165], v[204:207], v[36:39]
	v_mfma_f32_16x16x32_bf16 v[28:31], v[170:173], v[204:207], v[28:31]
	v_mfma_f32_16x16x32_bf16 v[20:23], v[162:165], v[212:215], v[20:23]
	v_mfma_f32_16x16x32_bf16 v[12:15], v[170:173], v[212:215], v[12:15]
	v_mfma_f32_16x16x32_bf16 v[4:7], v[162:165], v[226:229], v[4:7]
	v_mfma_f32_16x16x32_bf16 v[0:3], v[170:173], v[226:229], v[0:3]

.Lk0_rb2:
	s_add_u32 s30, s30, 0x40000
	s_addc_u32 s31, s31, 0
	s_mov_b32 m0, s62
	v_lshl_add_u64 v[192:193], s[30:31], 0, v[134:135]
	ds_read_b128 v[174:177], v145 offset:32768
	ds_read_b128 v[178:181], v145 offset:33792
	ds_read_b128 v[200:203], v145 offset:34816
	ds_read_b128 v[204:207], v145 offset:35840
	ds_read_b128 v[208:211], v145 offset:36864
	ds_read_b128 v[212:215], v145 offset:37888
	ds_read_b128 v[222:225], v145 offset:38912
	ds_read_b128 v[226:229], v145 offset:39936
	s_cmp_lg_u64 s[36:37], 0
	s_cbranch_scc1 .Ln3_w3_do
	s_cmp_eq_u32 s84, 12
	s_cbranch_scc1 .Ln3_w3
.Ln3_w3_do:
	global_load_lds_dwordx4 v[192:193], off
	v_lshl_add_u64 v[192:193], s[30:31], 0, v[132:133]
	s_mov_b32 m0, s63
	s_nop 0
	global_load_lds_dwordx4 v[192:193], off
	s_waitcnt vmcnt(8)
	s_cmp_lg_u32 s101, 1
	s_cbranch_scc1 .Lk0_w3
	s_waitcnt vmcnt(6)
.Lk0_w3:
	s_branch .Ln3_w3_j
.Ln3_w3:
	s_waitcnt vmcnt(0)
.Ln3_w3_j:
	s_waitcnt lgkmcnt(0)
	s_barrier
	s_setprio 1
	s_waitcnt lgkmcnt(0)
	s_cmp_eq_u32 s101, 1
	v_mfma_f32_16x16x32_bf16 v[126:129], v[140:143], v[174:177], v[126:129]
	v_mfma_f32_16x16x32_bf16 v[122:125], v[150:153], v[174:177], v[122:125]
	v_mfma_f32_16x16x32_bf16 v[114:117], v[140:143], v[200:203], v[114:117]
	v_mfma_f32_16x16x32_bf16 v[106:109], v[150:153], v[200:203], v[106:109]
	v_mfma_f32_16x16x32_bf16 v[98:101], v[140:143], v[208:211], v[98:101]
	v_mfma_f32_16x16x32_bf16 v[90:93], v[150:153], v[208:211], v[90:93]
	v_mfma_f32_16x16x32_bf16 v[82:85], v[140:143], v[222:225], v[82:85]
	v_mfma_f32_16x16x32_bf16 v[72:75], v[150:153], v[222:225], v[72:75]
	v_mfma_f32_16x16x32_bf16 v[126:129], v[146:149], v[178:181], v[126:129]
	v_mfma_f32_16x16x32_bf16 v[122:125], v[154:157], v[178:181], v[122:125]
	v_mfma_f32_16x16x32_bf16 v[114:117], v[146:149], v[204:207], v[114:117]
	v_mfma_f32_16x16x32_bf16 v[106:109], v[154:157], v[204:207], v[106:109]
	v_mfma_f32_16x16x32_bf16 v[98:101], v[146:149], v[212:215], v[98:101]
	v_mfma_f32_16x16x32_bf16 v[90:93], v[154:157], v[212:215], v[90:93]
	v_mfma_f32_16x16x32_bf16 v[82:85], v[146:149], v[226:229], v[82:85]
	v_mfma_f32_16x16x32_bf16 v[72:75], v[154:157], v[226:229], v[72:75]
	s_cbranch_scc1 .Lk0_half3
	v_mfma_f32_16x16x32_bf16 v[118:121], v[158:161], v[174:177], v[118:121]
	v_mfma_f32_16x16x32_bf16 v[110:113], v[166:169], v[174:177], v[110:113]
	v_mfma_f32_16x16x32_bf16 v[102:105], v[158:161], v[200:203], v[102:105]
	v_mfma_f32_16x16x32_bf16 v[94:97], v[166:169], v[200:203], v[94:97]
	v_mfma_f32_16x16x32_bf16 v[86:89], v[158:161], v[208:211], v[86:89]
	v_mfma_f32_16x16x32_bf16 v[76:79], v[166:169], v[208:211], v[76:79]
	v_mfma_f32_16x16x32_bf16 v[68:71], v[158:161], v[222:225], v[68:71]
	v_mfma_f32_16x16x32_bf16 v[64:67], v[166:169], v[222:225], v[64:67]
	v_mfma_f32_16x16x32_bf16 v[118:121], v[162:165], v[178:181], v[118:121]
	v_mfma_f32_16x16x32_bf16 v[110:113], v[170:173], v[178:181], v[110:113]
	v_mfma_f32_16x16x32_bf16 v[102:105], v[162:165], v[204:207], v[102:105]
	v_mfma_f32_16x16x32_bf16 v[94:97], v[170:173], v[204:207], v[94:97]
	v_mfma_f32_16x16x32_bf16 v[86:89], v[162:165], v[212:215], v[86:89]
	v_mfma_f32_16x16x32_bf16 v[76:79], v[170:173], v[212:215], v[76:79]
	v_mfma_f32_16x16x32_bf16 v[68:71], v[162:165], v[226:229], v[68:71]
	v_mfma_f32_16x16x32_bf16 v[64:67], v[170:173], v[226:229], v[64:67]
.Lk0_half3:
	s_setprio 0
	s_barrier
	s_add_i32 s30, s85, s39
	v_lshl_add_u64 v[182:183], v[182:183], 0, s[12:13]
	s_mov_b32 m0, s30
	ds_read_b128 v[174:177], v145 offset:49152
	ds_read_b128 v[178:181], v145 offset:50176
	ds_read_b128 v[200:203], v145 offset:51200
	ds_read_b128 v[204:207], v145 offset:52224
	ds_read_b128 v[208:211], v145 offset:53248
	ds_read_b128 v[212:215], v145 offset:54272
	ds_read_b128 v[222:225], v145 offset:55296
	ds_read_b128 v[226:229], v145 offset:56320
	s_cmp_lg_u64 s[36:37], 0
	s_cbranch_scc1 .Ln3_w4_do
	s_cmp_eq_u32 s84, 12
	s_cbranch_scc1 .Ln3_w4
.Ln3_w4_do:
	global_load_lds_dwordx4 v[182:183], off
	s_add_i32 m0, s30, 0x2000
	s_add_u32 s6, s6, 0x40080
	v_lshl_add_u64 v[182:183], v[184:185], 0, s[12:13]
	s_addc_u32 s7, s7, 0
	s_add_i32 s30, s86, s39
	global_load_lds_dwordx4 v[182:183], off
	s_cmp_eq_u32 s101, 1
	s_cbranch_scc1 .Lk0_nb1b
	v_lshl_add_u64 v[182:183], s[6:7], 0, v[80:81]
	s_mov_b32 m0, s30
	s_nop 0
	global_load_lds_dwordx4 v[182:183], off
	v_lshl_add_u64 v[182:183], s[6:7], 0, v[130:131]
	s_add_i32 m0, s30, 0x2000
	s_nop 0
	global_load_lds_dwordx4 v[182:183], off
.Lk0_nb1b:
	v_lshl_add_u64 v[182:183], v[188:189], 0, s[12:13]
	s_mov_b32 m0, s66
	s_nop 0
	global_load_lds_dwordx4 v[182:183], off
	v_lshl_add_u64 v[182:183], v[190:191], 0, s[12:13]
	s_mov_b32 m0, s67
	s_nop 0
	global_load_lds_dwordx4 v[182:183], off
	s_waitcnt vmcnt(8)
	s_cmp_lg_u32 s101, 1
	s_cbranch_scc1 .Lk0_w4
	s_waitcnt vmcnt(6)
.Lk0_w4:
	s_branch .Ln3_w4_j
.Ln3_w4:
.Ln3_w4_j:
	s_waitcnt lgkmcnt(0)
	s_barrier
	s_setprio 1
	s_waitcnt lgkmcnt(0)
	s_cmp_eq_u32 s101, 1
	v_mfma_f32_16x16x32_bf16 v[60:63], v[140:143], v[174:177], v[60:63]
	v_mfma_f32_16x16x32_bf16 v[56:59], v[150:153], v[174:177], v[56:59]
	v_mfma_f32_16x16x32_bf16 v[48:51], v[140:143], v[200:203], v[48:51]
	v_mfma_f32_16x16x32_bf16 v[40:43], v[150:153], v[200:203], v[40:43]
	v_mfma_f32_16x16x32_bf16 v[32:35], v[140:143], v[208:211], v[32:35]
	v_mfma_f32_16x16x32_bf16 v[24:27], v[150:153], v[208:211], v[24:27]
	v_mfma_f32_16x16x32_bf16 v[16:19], v[140:143], v[222:225], v[16:19]
	v_mfma_f32_16x16x32_bf16 v[8:11], v[150:153], v[222:225], v[8:11]
	v_mfma_f32_16x16x32_bf16 v[60:63], v[146:149], v[178:181], v[60:63]
	v_mfma_f32_16x16x32_bf16 v[56:59], v[154:157], v[178:181], v[56:59]
	v_mfma_f32_16x16x32_bf16 v[48:51], v[146:149], v[204:207], v[48:51]
	v_mfma_f32_16x16x32_bf16 v[40:43], v[154:157], v[204:207], v[40:43]
	v_mfma_f32_16x16x32_bf16 v[32:35], v[146:149], v[212:215], v[32:35]
	v_mfma_f32_16x16x32_bf16 v[24:27], v[154:157], v[212:215], v[24:27]
	v_mfma_f32_16x16x32_bf16 v[16:19], v[146:149], v[226:229], v[16:19]
	v_mfma_f32_16x16x32_bf16 v[8:11], v[154:157], v[226:229], v[8:11]
	s_cbranch_scc1 .Lk0_half4
	v_mfma_f32_16x16x32_bf16 v[52:55], v[158:161], v[174:177], v[52:55]
	v_mfma_f32_16x16x32_bf16 v[44:47], v[166:169], v[174:177], v[44:47]
	v_mfma_f32_16x16x32_bf16 v[36:39], v[158:161], v[200:203], v[36:39]
	v_mfma_f32_16x16x32_bf16 v[28:31], v[166:169], v[200:203], v[28:31]
	v_mfma_f32_16x16x32_bf16 v[20:23], v[158:161], v[208:211], v[20:23]
	v_mfma_f32_16x16x32_bf16 v[12:15], v[166:169], v[208:211], v[12:15]
	v_mfma_f32_16x16x32_bf16 v[4:7], v[158:161], v[222:225], v[4:7]
	v_mfma_f32_16x16x32_bf16 v[0:3], v[166:169], v[222:225], v[0:3]
	v_mfma_f32_16x16x32_bf16 v[52:55], v[162:165], v[178:181], v[52:55]
	v_mfma_f32_16x16x32_bf16 v[44:47], v[170:173], v[178:181], v[44:47]
	v_mfma_f32_16x16x32_bf16 v[36:39], v[162:165], v[204:207], v[36:39]
	v_mfma_f32_16x16x32_bf16 v[28:31], v[170:173], v[204:207], v[28:31]
	v_mfma_f32_16x16x32_bf16 v[20:23], v[162:165], v[212:215], v[20:23]
	v_mfma_f32_16x16x32_bf16 v[12:15], v[170:173], v[212:215], v[12:15]
	v_mfma_f32_16x16x32_bf16 v[4:7], v[162:165], v[226:229], v[4:7]
	v_mfma_f32_16x16x32_bf16 v[0:3], v[170:173], v[226:229], v[0:3]
